# baseline (speedup 1.0000x reference)
; DEV int otid() { int t = (int)threadIdx.x; asm volatile("" : "+v"(t)); return t; }
; DEV float bf2f(u16 b) { return __uint_as_float(((unsigned)b) << 16); }
; DEV u16 f2bf(float f) { return (u16)(cvt_pk_bf16(f, 0.f) & 0xffffu); }
; DEV float wsum(float v) { for (int o = 32; o > 0; o >>= 1) v += __shfl_xor(v, o); return v; }
; DEV void gmlp_unit(LAS unsigned char* lds, const P& p, int c, int g) {
;     ...
;     const int tid = otid(), wid = __builtin_amdgcn_readfirstlane(tid >> 6), lane = tid & 63, fr = lane & 15, fq = lane >> 4;
;     float lg[8], lb[8];
; #pragma unroll
;     for (int e = 0; e < 8; ++e) { lg[e] = p.gm_ln_g[g * 512 + lane + 64 * e]; lb[e] = p.gm_ln_b[g * 512 + lane + 64 * e]; }
; #pragma unroll 4
;     for (int jr = 0; jr < 16; ++jr) { const int j = wid * 16 + jr; const u16* vr = UV + (size_t)(c * 128 + j) * 4096 + 2048 + g * 512;
;         float v[8]; float sm = 0.f;
; #pragma unroll
;         for (int e = 0; e < 8; ++e) { v[e] = bf2f(vr[lane + 64 * e]); sm += v[e]; }
;         const float mu = wsum(sm) * (1.0f / 512.0f); float sq = 0.f;
; #pragma unroll
;         for (int e = 0; e < 8; ++e) { v[e] -= mu; sq += v[e] * v[e]; }
;         const float rs = rsqrtf(wsum(sq) * (1.0f / 512.0f) + EPS);
; #pragma unroll
;         for (int e = 0; e < 8; ++e) VnT[(lane + 64 * e) * VS + j] = f2bf(v[e] * rs * lg[e] + lb[e]); }
.LBB0_518:
	s_and_b32 s4, s9, 3
	v_mov_b32_e32 v9, v198
	s_lshl_b32 s5, s4, 9
	v_and_b32_e32 v8, 63, v9
	v_or_b32_e32 v0, s5, v8
	v_readlane_b32 s12, v251, 21
	v_lshlrev_b32_e32 v0, 2, v0
	v_readlane_b32 s13, v251, 22
	v_readlane_b32 s14, v251, 23
	v_readlane_b32 s15, v251, 24
	s_nop 2
	global_load_dword v10, v0, s[12:13]
	s_nop 0
	global_load_dword v11, v0, s[14:15]
	global_load_dword v12, v0, s[12:13] offset:256
	global_load_dword v13, v0, s[14:15] offset:256
	global_load_dword v14, v0, s[12:13] offset:512
	global_load_dword v15, v0, s[14:15] offset:512
	global_load_dword v16, v0, s[12:13] offset:768
	global_load_dword v17, v0, s[14:15] offset:768
	global_load_dword v18, v0, s[12:13] offset:1024
	global_load_dword v19, v0, s[14:15] offset:1024
	global_load_dword v20, v0, s[12:13] offset:1280
	global_load_dword v21, v0, s[14:15] offset:1280
	global_load_dword v22, v0, s[12:13] offset:1536
	global_load_dword v23, v0, s[14:15] offset:1536
	global_load_dword v24, v0, s[12:13] offset:1792
	global_load_dword v25, v0, s[14:15] offset:1792
	v_cmp_lt_i32_e32 vcc, v207, v206
	s_and_b32 s1, s8, 3
	v_readfirstlane_b32 s10, v9
	v_cndmask_b32_e32 v0, v204, v207, vcc
	v_cmp_lt_i32_e32 vcc, v208, v206
	s_lshl_b32 s11, s1, 10
	s_ashr_i32 s1, s10, 2
	v_lshlrev_b32_e32 v26, 2, v0
	v_cndmask_b32_e32 v0, v204, v208, vcc
	v_cmp_lt_i32_e32 vcc, v209, v206
	s_and_b32 s12, s1, -16
	v_lshlrev_b32_e32 v27, 2, v0
	v_cndmask_b32_e32 v0, v204, v209, vcc
	v_cmp_lt_i32_e32 vcc, v210, v206
	s_lshl_b32 s1, s1, 1
	v_lshlrev_b32_e32 v28, 2, v0
	v_cndmask_b32_e32 v0, v204, v210, vcc
	v_cmp_lt_i32_e32 vcc, v211, v206
	s_andn2_b32 s1, s1, 31
	v_lshlrev_b32_e32 v29, 2, v0
	v_cndmask_b32_e32 v0, v204, v211, vcc
	v_cmp_lt_i32_e32 vcc, v212, v206
	s_add_i32 s1, s1, 0
	s_and_b32 s0, s6, 0xffffff80
	v_lshlrev_b32_e32 v30, 2, v0
	v_cndmask_b32_e32 v0, v204, v212, vcc
	s_add_i32 s1, s1, 0x10400
	v_lshlrev_b32_e32 v31, 2, v0
	v_mov_b32_e32 v0, s1
	s_movk_i32 s1, 0x104
	s_add_i32 s0, s0, s12
	v_mad_u32_u24 v32, v8, s1, v0
	s_ashr_i32 s1, s0, 31
	s_lshl_b64 s[0:1], s[0:1], 13
	s_or_b32 s0, s0, s11
	s_add_u32 s0, s90, s0
	v_lshlrev_b32_e32 v160, 1, v8
	s_addc_u32 s1, s91, s1
	s_waitcnt lgkmcnt(0)
	v_lshl_add_u64 v[0:1], s[0:1], 0, v[160:161]
	s_mov_b64 s[0:1], 0
	s_mov_b32 s12, 0x800000
	v_readlane_b32 s16, v251, 25
	v_readlane_b32 s17, v251, 26
	v_readlane_b32 s18, v251, 27
	v_readlane_b32 s19, v251, 28
	v_readlane_b32 s20, v251, 29
	v_readlane_b32 s21, v251, 30
	v_readlane_b32 s22, v251, 31
	v_readlane_b32 s23, v251, 32
	v_readlane_b32 s24, v251, 33
	v_readlane_b32 s25, v251, 34
	v_readlane_b32 s26, v251, 35
	v_readlane_b32 s27, v251, 36
	v_and_b32_e32 v3, 7, v8
	v_lshlrev_b32_e32 v3, 7, v3
	v_lshlrev_b32_e32 v4, 1, v8
	v_sub_u32_e32 v3, v3, v4
	v_lshrrev_b32_e32 v2, 3, v8
	v_and_b32_e32 v5, 3, v2
	v_lshl_add_u32 v2, v2, 13, v3
	v_lshl_add_u32 v4, v5, 13, v3
	v_ashrrev_i32_e32 v3, 31, v2
	v_ashrrev_i32_e32 v5, 31, v4
	v_lshl_add_u64 v[2:3], v[0:1], 0, v[2:3]
	v_lshl_add_u64 v[120:121], v[0:1], 0, v[4:5]
	v_add_co_u32_e32 v2, vcc, 0x1bf21000, v2
	s_nop 1
	v_addc_co_u32_e32 v3, vcc, 0, v3, vcc
	v_add_co_u32_e32 v120, vcc, 0x1bf29000, v120
	s_nop 1
	v_addc_co_u32_e32 v121, vcc, 0, v121, vcc
	global_load_dword v6, v[2:3], off
	v_add_co_u32_e32 v2, vcc, 0x10000, v2
	s_nop 1
	v_addc_co_u32_e32 v3, vcc, 0, v3, vcc
	global_load_dword v6, v[2:3], off
.LBB0_519:
	v_lshl_add_u64 v[2:3], v[0:1], 0, s[0:1]
	v_lshl_add_u64 v[122:123], v[120:121], 0, s[0:1]
	global_load_dword v6, v[122:123], off
	v_add_co_u32_e32 v4, vcc, 0x1bf21000, v2
	s_mov_b32 s11, 0x1bf23000
	s_nop 0
	v_addc_co_u32_e32 v5, vcc, 0, v3, vcc
	global_load_ushort v6, v[4:5], off
	global_load_ushort v7, v[4:5], off offset:128
	v_add_u32_e32 v47, 0x4100, v32
	v_add_u32_e32 v49, 0x8200, v32
	s_add_u32 s0, s0, 0x8000
	s_addc_u32 s1, s1, 0
	v_add_u32_e32 v46, 0xffffbf00, v32
	v_add_u32_e32 v51, 0xc300, v32
	s_cmp_eq_u32 s0, 0x20000
	s_waitcnt vmcnt(0)
	v_lshlrev_b32_e32 v33, 16, v6
	v_lshlrev_b32_e32 v37, 16, v7
	global_load_ushort v7, v[4:5], off offset:256
	v_add_f32_e32 v6, 0, v33
	v_add_f32_e32 v6, v6, v37
	s_waitcnt vmcnt(0)
	v_lshlrev_b32_e32 v38, 16, v7
	global_load_ushort v7, v[4:5], off offset:384
	v_add_f32_e32 v6, v6, v38
	s_waitcnt vmcnt(0)
	v_lshlrev_b32_e32 v40, 16, v7
	global_load_ushort v7, v[4:5], off offset:896
	global_load_ushort v34, v[4:5], off offset:768
	v_add_f32_e32 v6, v6, v40
	s_waitcnt vmcnt(0)
	v_lshlrev_b32_e32 v35, 16, v34
	v_lshlrev_b32_e32 v34, 16, v7
	global_load_ushort v7, v[4:5], off offset:640
	s_nop 0
	global_load_ushort v4, v[4:5], off offset:512
	s_waitcnt vmcnt(0)
	v_lshlrev_b32_e32 v5, 16, v4
	v_lshlrev_b32_e32 v4, 16, v7
	v_add_f32_e32 v6, v6, v5
	v_add_f32_e32 v6, v6, v4
	v_add_f32_e32 v6, v6, v35
	v_add_f32_e32 v6, v6, v34
	ds_bpermute_b32 v7, v26, v6
	s_waitcnt lgkmcnt(0)
	v_add_f32_e32 v6, v6, v7
	ds_bpermute_b32 v7, v27, v6
	s_waitcnt lgkmcnt(0)
	v_add_f32_e32 v6, v6, v7
	ds_bpermute_b32 v7, v28, v6
	s_waitcnt lgkmcnt(0)
	v_add_f32_e32 v6, v6, v7
	ds_bpermute_b32 v7, v29, v6
	s_waitcnt lgkmcnt(0)
	v_add_f32_e32 v6, v6, v7
	ds_bpermute_b32 v7, v30, v6
	s_waitcnt lgkmcnt(0)
	v_add_f32_e32 v6, v6, v7
	ds_bpermute_b32 v7, v31, v6
	s_waitcnt lgkmcnt(0)
	v_add_f32_e32 v6, v6, v7
	v_fmac_f32_e32 v37, 0xbb000000, v6
	v_fmac_f32_e32 v33, 0xbb000000, v6
	v_mul_f32_e32 v39, v37, v37
	v_mul_f32_e32 v36, 0x3b000000, v6
	v_fmac_f32_e32 v39, v33, v33
	v_fmac_f32_e32 v38, 0xbb000000, v6
	v_fmac_f32_e32 v39, v38, v38
	v_fmac_f32_e32 v40, 0xbb000000, v6
	v_pk_add_f32 v[6:7], v[4:5], v[36:37] op_sel_hi:[1,0] neg_lo:[0,1] neg_hi:[0,1]
	v_fmac_f32_e32 v39, v40, v40
	v_pk_mul_f32 v[4:5], v[6:7], v[6:7]
	s_nop 0
	v_add_f32_e32 v5, v5, v39
	v_add_f32_e32 v39, v4, v5
	v_pk_add_f32 v[4:5], v[34:35], v[36:37] op_sel_hi:[1,0] neg_lo:[0,1] neg_hi:[0,1]
	s_nop 0
	v_pk_mul_f32 v[34:35], v[4:5], v[4:5]
	s_nop 0
	v_add_f32_e32 v35, v35, v39
	v_add_f32_e32 v34, v34, v35
	ds_bpermute_b32 v35, v26, v34
	v_add_u32_e32 v39, 0xffff7e00, v32
	s_waitcnt lgkmcnt(0)
; DEV float bf2f(u16 b) { return __uint_as_float(((unsigned)b) << 16); }
; DEV u16 f2bf(float f) { return (u16)(cvt_pk_bf16(f, 0.f) & 0xffffu); }
; DEV float wsum(float v) { for (int o = 32; o > 0; o >>= 1) v += __shfl_xor(v, o); return v; }
; DEV void gmlp_unit(LAS unsigned char* lds, const P& p, int c, int g) {
;     ...
;     for (int jr = 0; jr < 16; ++jr) { const int j = wid * 16 + jr; const u16* vr = UV + (size_t)(c * 128 + j) * 4096 + 2048 + g * 512;
;         float v[8]; float sm = 0.f;
; #pragma unroll
;         for (int e = 0; e < 8; ++e) { v[e] = bf2f(vr[lane + 64 * e]); sm += v[e]; }
;         const float mu = wsum(sm) * (1.0f / 512.0f); float sq = 0.f;
; #pragma unroll
;         for (int e = 0; e < 8; ++e) { v[e] -= mu; sq += v[e] * v[e]; }
;         const float rs = rsqrtf(wsum(sq) * (1.0f / 512.0f) + EPS);
; #pragma unroll
;         for (int e = 0; e < 8; ++e) VnT[(lane + 64 * e) * VS + j] = f2bf(v[e] * rs * lg[e] + lb[e]); }
	v_add_f32_e32 v34, v34, v35
	ds_bpermute_b32 v35, v27, v34
	s_waitcnt lgkmcnt(0)
	v_add_f32_e32 v34, v34, v35
	ds_bpermute_b32 v35, v28, v34
	s_waitcnt lgkmcnt(0)
	v_add_f32_e32 v34, v34, v35
	ds_bpermute_b32 v35, v29, v34
	s_waitcnt lgkmcnt(0)
	v_add_f32_e32 v34, v34, v35
	ds_bpermute_b32 v35, v30, v34
	s_waitcnt lgkmcnt(0)
	v_add_f32_e32 v34, v34, v35
	ds_bpermute_b32 v35, v31, v34
	s_waitcnt lgkmcnt(0)
	v_add_f32_e32 v34, v34, v35
	v_fmamk_f32 v34, v34, 0x3b000000, v199
	v_cmp_gt_f32_e32 vcc, s12, v34
	v_mul_f32_e32 v35, 0x4b800000, v34
	s_nop 0
	v_cndmask_b32_e32 v34, v34, v35, vcc
	v_rsq_f32_e32 v34, v34
	s_nop 0
	v_mul_f32_e32 v35, 0x45800000, v34
	v_cndmask_b32_e32 v41, v34, v35, vcc
	v_mul_f32_e32 v4, v4, v41
	v_mul_f32_e32 v5, v5, v41
	v_fma_f32 v50, v24, v4, v25
	v_add_co_u32_e32 v4, vcc, s11, v2
	v_fma_f32 v48, v22, v5, v23
	s_nop 0
	v_addc_co_u32_e32 v5, vcc, 0, v3, vcc
	v_mul_f32_e32 v33, v33, v41
	v_mul_f32_e32 v34, v37, v41
	v_mul_f32_e32 v36, v38, v41
	v_mul_f32_e32 v38, v40, v41
	v_mul_f32_e32 v7, v7, v41
	v_mul_f32_e32 v6, v6, v41
	global_load_ushort v40, v[4:5], off
	global_load_ushort v41, v[4:5], off offset:128
	s_mov_b32 s11, 0x1bf25000
	v_fma_f32 v33, v10, v33, v11
	v_add_u32_e32 v35, 0xfffefc00, v32
	v_fma_f32 v7, v18, v7, v19
	v_fma_f32 v34, v12, v34, v13
	v_fma_f32 v6, v20, v6, v21
	v_add_u32_e32 v37, 0xffff3d00, v32
	v_fma_f32 v36, v14, v36, v15
	v_fma_f32 v38, v16, v38, v17
	s_waitcnt vmcnt(1)
	v_lshlrev_b32_e32 v52, 16, v40
	s_waitcnt vmcnt(0)
	v_lshlrev_b32_e32 v53, 16, v41
	global_load_ushort v41, v[4:5], off offset:256
	v_add_f32_e32 v40, 0, v52
	v_add_f32_e32 v40, v40, v53
	s_waitcnt vmcnt(0)
	v_lshlrev_b32_e32 v54, 16, v41
	global_load_ushort v41, v[4:5], off offset:384
	v_add_f32_e32 v40, v40, v54
	s_waitcnt vmcnt(0)
	v_lshlrev_b32_e32 v55, 16, v41
	v_add_f32_e32 v42, v40, v55
	global_load_ushort v40, v[4:5], off offset:896
	global_load_ushort v41, v[4:5], off offset:768
	global_load_ushort v43, v[4:5], off offset:640
	s_nop 0
	global_load_ushort v4, v[4:5], off offset:512
	s_waitcnt vmcnt(3)
	v_lshlrev_b32_e32 v40, 16, v40
	s_waitcnt vmcnt(2)
	v_lshlrev_b32_e32 v41, 16, v41
	s_waitcnt vmcnt(0)
	v_lshlrev_b32_e32 v5, 16, v4
	v_lshlrev_b32_e32 v4, 16, v43
	v_add_f32_e32 v42, v42, v5
	v_add_f32_e32 v42, v42, v4
	v_add_f32_e32 v42, v42, v41
	v_add_f32_e32 v42, v42, v40
	ds_bpermute_b32 v43, v26, v42
	s_waitcnt lgkmcnt(0)
	v_add_f32_e32 v42, v42, v43
	ds_bpermute_b32 v43, v27, v42
	s_waitcnt lgkmcnt(0)
	v_add_f32_e32 v42, v42, v43
	ds_bpermute_b32 v43, v28, v42
	s_waitcnt lgkmcnt(0)
	v_add_f32_e32 v42, v42, v43
	ds_bpermute_b32 v43, v29, v42
	s_waitcnt lgkmcnt(0)
	v_add_f32_e32 v42, v42, v43
	ds_bpermute_b32 v43, v30, v42
	s_waitcnt lgkmcnt(0)
	v_add_f32_e32 v42, v42, v43
	ds_bpermute_b32 v43, v31, v42
	s_waitcnt lgkmcnt(0)
	v_add_f32_e32 v43, v42, v43
	v_fmac_f32_e32 v53, 0xbb000000, v43
	v_fmac_f32_e32 v52, 0xbb000000, v43
	v_mul_f32_e32 v56, v53, v53
	v_mul_f32_e32 v42, 0x3b000000, v43
	v_fmac_f32_e32 v56, v52, v52
	v_fmac_f32_e32 v54, 0xbb000000, v43
	v_fmac_f32_e32 v56, v54, v54
	v_fmac_f32_e32 v55, 0xbb000000, v43
	v_pk_add_f32 v[4:5], v[4:5], v[42:43] op_sel_hi:[1,0] neg_lo:[0,1] neg_hi:[0,1]
	v_fmac_f32_e32 v56, v55, v55
	v_pk_mul_f32 v[44:45], v[4:5], v[4:5]
	s_nop 0
	v_add_f32_e32 v43, v45, v56
	v_pk_add_f32 v[40:41], v[40:41], v[42:43] op_sel_hi:[1,0] neg_lo:[0,1] neg_hi:[0,1]
	v_add_f32_e32 v44, v44, v43
	v_pk_mul_f32 v[42:43], v[40:41], v[40:41]
	s_nop 0
	v_add_f32_e32 v43, v43, v44
	v_add_f32_e32 v42, v42, v43
	ds_bpermute_b32 v43, v26, v42
	s_waitcnt lgkmcnt(0)
	v_add_f32_e32 v42, v42, v43
	ds_bpermute_b32 v43, v27, v42
	s_waitcnt lgkmcnt(0)
	v_add_f32_e32 v42, v42, v43
	ds_bpermute_b32 v43, v28, v42
	s_waitcnt lgkmcnt(0)
	v_add_f32_e32 v42, v42, v43
	ds_bpermute_b32 v43, v29, v42
	s_waitcnt lgkmcnt(0)
	v_add_f32_e32 v42, v42, v43
	ds_bpermute_b32 v43, v30, v42
	s_waitcnt lgkmcnt(0)
	v_add_f32_e32 v42, v42, v43
	ds_bpermute_b32 v43, v31, v42
	s_waitcnt lgkmcnt(0)
	v_add_f32_e32 v42, v42, v43
	v_fmamk_f32 v42, v42, 0x3b000000, v199
	v_cmp_gt_f32_e32 vcc, s12, v42
	v_mul_f32_e32 v43, 0x4b800000, v42
	s_nop 0
	v_cndmask_b32_e32 v42, v42, v43, vcc
	v_rsq_f32_e32 v42, v42
	s_nop 0
	v_mul_f32_e32 v43, 0x45800000, v42
	v_cndmask_b32_e32 v42, v42, v43, vcc
	v_mul_f32_e32 v4, v4, v42
	v_fma_f32 v57, v20, v4, v21
	v_mul_f32_e32 v4, v41, v42
	v_fma_f32 v58, v22, v4, v23
	v_mul_f32_e32 v4, v40, v42
	v_mul_f32_e32 v5, v5, v42
	v_fma_f32 v59, v24, v4, v25
	v_add_co_u32_e32 v4, vcc, s11, v2
	v_fma_f32 v56, v18, v5, v19
	s_nop 0
	v_addc_co_u32_e32 v5, vcc, 0, v3, vcc
	global_load_ushort v40, v[4:5], off
	global_load_ushort v41, v[4:5], off offset:128
	v_mul_f32_e32 v43, v52, v42
	v_fma_f32 v52, v10, v43, v11
	v_mul_f32_e32 v43, v53, v42
	v_fma_f32 v53, v12, v43, v13
	v_mul_f32_e32 v43, v54, v42
	v_fma_f32 v54, v14, v43, v15
	v_mul_f32_e32 v43, v55, v42
	v_fma_f32 v55, v16, v43, v17
	s_mov_b32 s11, 0x1bf27000
	v_cvt_pk_bf16_f32 v33, v33, v52
	v_cvt_pk_bf16_f32 v7, v7, v56
	v_cvt_pk_bf16_f32 v34, v34, v53
	s_waitcnt vmcnt(1)
	v_lshlrev_b32_e32 v60, 16, v40
	s_waitcnt vmcnt(0)
	v_lshlrev_b32_e32 v61, 16, v41
	global_load_ushort v41, v[4:5], off offset:256
	v_add_f32_e32 v40, 0, v60
	v_add_f32_e32 v40, v40, v61
	s_waitcnt vmcnt(0)
	v_lshlrev_b32_e32 v62, 16, v41
	global_load_ushort v41, v[4:5], off offset:384
	v_add_f32_e32 v40, v40, v62
	s_waitcnt vmcnt(0)
	v_lshlrev_b32_e32 v63, 16, v41
	v_add_f32_e32 v42, v40, v63
	global_load_ushort v40, v[4:5], off offset:896
	global_load_ushort v41, v[4:5], off offset:768
	global_load_ushort v43, v[4:5], off offset:640
	s_nop 0
	global_load_ushort v4, v[4:5], off offset:512
	s_waitcnt vmcnt(3)
; DEV float bf2f(u16 b) { return __uint_as_float(((unsigned)b) << 16); }
; DEV u16 f2bf(float f) { return (u16)(cvt_pk_bf16(f, 0.f) & 0xffffu); }
; DEV float wsum(float v) { for (int o = 32; o > 0; o >>= 1) v += __shfl_xor(v, o); return v; }
; DEV void gmlp_unit(LAS unsigned char* lds, const P& p, int c, int g) {
;     ...
;     for (int jr = 0; jr < 16; ++jr) { const int j = wid * 16 + jr; const u16* vr = UV + (size_t)(c * 128 + j) * 4096 + 2048 + g * 512;
;         float v[8]; float sm = 0.f;
; #pragma unroll
;         for (int e = 0; e < 8; ++e) { v[e] = bf2f(vr[lane + 64 * e]); sm += v[e]; }
;         const float mu = wsum(sm) * (1.0f / 512.0f); float sq = 0.f;
; #pragma unroll
;         for (int e = 0; e < 8; ++e) { v[e] -= mu; sq += v[e] * v[e]; }
;         const float rs = rsqrtf(wsum(sq) * (1.0f / 512.0f) + EPS);
; #pragma unroll
;         for (int e = 0; e < 8; ++e) VnT[(lane + 64 * e) * VS + j] = f2bf(v[e] * rs * lg[e] + lb[e]); }
	v_lshlrev_b32_e32 v40, 16, v40
	s_waitcnt vmcnt(2)
	v_lshlrev_b32_e32 v41, 16, v41
	s_waitcnt vmcnt(0)
	v_lshlrev_b32_e32 v5, 16, v4
	v_lshlrev_b32_e32 v4, 16, v43
	v_add_f32_e32 v42, v42, v5
	v_add_f32_e32 v42, v42, v4
	v_add_f32_e32 v42, v42, v41
	v_add_f32_e32 v42, v42, v40
	ds_bpermute_b32 v43, v26, v42
	s_waitcnt lgkmcnt(0)
	v_add_f32_e32 v42, v42, v43
	ds_bpermute_b32 v43, v27, v42
	s_waitcnt lgkmcnt(0)
	v_add_f32_e32 v42, v42, v43
	ds_bpermute_b32 v43, v28, v42
	s_waitcnt lgkmcnt(0)
	v_add_f32_e32 v42, v42, v43
	ds_bpermute_b32 v43, v29, v42
	s_waitcnt lgkmcnt(0)
	v_add_f32_e32 v42, v42, v43
	ds_bpermute_b32 v43, v30, v42
	s_waitcnt lgkmcnt(0)
	v_add_f32_e32 v42, v42, v43
	ds_bpermute_b32 v43, v31, v42
	s_waitcnt lgkmcnt(0)
	v_add_f32_e32 v43, v42, v43
	v_fmac_f32_e32 v61, 0xbb000000, v43
	v_fmac_f32_e32 v60, 0xbb000000, v43
	v_mul_f32_e32 v64, v61, v61
	v_mul_f32_e32 v42, 0x3b000000, v43
	v_fmac_f32_e32 v64, v60, v60
	v_fmac_f32_e32 v62, 0xbb000000, v43
	v_fmac_f32_e32 v64, v62, v62
	v_fmac_f32_e32 v63, 0xbb000000, v43
	v_pk_add_f32 v[4:5], v[4:5], v[42:43] op_sel_hi:[1,0] neg_lo:[0,1] neg_hi:[0,1]
	v_fmac_f32_e32 v64, v63, v63
	v_pk_mul_f32 v[44:45], v[4:5], v[4:5]
	s_nop 0
	v_add_f32_e32 v43, v45, v64
	v_pk_add_f32 v[40:41], v[40:41], v[42:43] op_sel_hi:[1,0] neg_lo:[0,1] neg_hi:[0,1]
	v_add_f32_e32 v44, v44, v43
	v_pk_mul_f32 v[42:43], v[40:41], v[40:41]
	s_nop 0
	v_add_f32_e32 v43, v43, v44
	v_add_f32_e32 v42, v42, v43
	ds_bpermute_b32 v43, v26, v42
	s_waitcnt lgkmcnt(0)
	v_add_f32_e32 v42, v42, v43
	ds_bpermute_b32 v43, v27, v42
	s_waitcnt lgkmcnt(0)
	v_add_f32_e32 v42, v42, v43
	ds_bpermute_b32 v43, v28, v42
	s_waitcnt lgkmcnt(0)
	v_add_f32_e32 v42, v42, v43
	ds_bpermute_b32 v43, v29, v42
	s_waitcnt lgkmcnt(0)
	v_add_f32_e32 v42, v42, v43
	ds_bpermute_b32 v43, v30, v42
	s_waitcnt lgkmcnt(0)
	v_add_f32_e32 v42, v42, v43
	ds_bpermute_b32 v43, v31, v42
	s_waitcnt lgkmcnt(0)
	v_add_f32_e32 v42, v42, v43
	v_fmamk_f32 v42, v42, 0x3b000000, v199
	v_cmp_gt_f32_e32 vcc, s12, v42
	v_mul_f32_e32 v43, 0x4b800000, v42
	s_nop 0
	v_cndmask_b32_e32 v42, v42, v43, vcc
	v_rsq_f32_e32 v42, v42
	s_nop 0
	v_mul_f32_e32 v43, 0x45800000, v42
	v_cndmask_b32_e32 v42, v42, v43, vcc
	v_mul_f32_e32 v43, v60, v42
	v_fma_f32 v44, v10, v43, v11
	v_mul_f32_e32 v43, v61, v42
	v_fma_f32 v45, v12, v43, v13
	v_mul_f32_e32 v43, v62, v42
	v_mul_f32_e32 v4, v4, v42
	v_fma_f32 v60, v14, v43, v15
	v_mul_f32_e32 v43, v63, v42
	v_fma_f32 v63, v20, v4, v21
	v_mul_f32_e32 v4, v41, v42
	v_add_co_u32_e32 v2, vcc, s11, v2
	v_mul_f32_e32 v5, v5, v42
	v_fma_f32 v64, v22, v4, v23
	v_mul_f32_e32 v4, v40, v42
	v_addc_co_u32_e32 v3, vcc, 0, v3, vcc
	v_fma_f32 v62, v18, v5, v19
	v_fma_f32 v65, v24, v4, v25
	global_load_ushort v4, v[2:3], off
	global_load_ushort v5, v[2:3], off offset:128
	v_fma_f32 v61, v16, v43, v17
	s_waitcnt vmcnt(1)
	v_lshlrev_b32_e32 v66, 16, v4
	s_waitcnt vmcnt(0)
	v_lshlrev_b32_e32 v67, 16, v5
	global_load_ushort v5, v[2:3], off offset:256
	v_add_f32_e32 v4, 0, v66
	v_add_f32_e32 v4, v4, v67
	s_waitcnt vmcnt(0)
	v_lshlrev_b32_e32 v68, 16, v5
	global_load_ushort v5, v[2:3], off offset:384
	v_add_f32_e32 v4, v4, v68
	s_waitcnt vmcnt(0)
	v_lshlrev_b32_e32 v69, 16, v5
	v_add_f32_e32 v40, v4, v69
	global_load_ushort v4, v[2:3], off offset:896
	global_load_ushort v5, v[2:3], off offset:768
	global_load_ushort v41, v[2:3], off offset:640
	s_nop 0
	global_load_ushort v2, v[2:3], off offset:512
	s_waitcnt vmcnt(3)
	v_lshlrev_b32_e32 v4, 16, v4
	s_waitcnt vmcnt(2)
	v_lshlrev_b32_e32 v5, 16, v5
	s_waitcnt vmcnt(0)
	v_lshlrev_b32_e32 v3, 16, v2
	v_lshlrev_b32_e32 v2, 16, v41
	v_add_f32_e32 v40, v40, v3
	v_add_f32_e32 v40, v40, v2
	v_add_f32_e32 v40, v40, v5
	v_add_f32_e32 v40, v40, v4
	ds_bpermute_b32 v41, v26, v40
	s_waitcnt lgkmcnt(0)
	v_add_f32_e32 v40, v40, v41
	ds_bpermute_b32 v41, v27, v40
	s_waitcnt lgkmcnt(0)
	v_add_f32_e32 v40, v40, v41
	ds_bpermute_b32 v41, v28, v40
	s_waitcnt lgkmcnt(0)
	v_add_f32_e32 v40, v40, v41
	ds_bpermute_b32 v41, v29, v40
	s_waitcnt lgkmcnt(0)
	v_add_f32_e32 v40, v40, v41
	ds_bpermute_b32 v41, v30, v40
	s_waitcnt lgkmcnt(0)
	v_add_f32_e32 v40, v40, v41
	ds_bpermute_b32 v41, v31, v40
	s_waitcnt lgkmcnt(0)
	v_add_f32_e32 v41, v40, v41
	v_fmac_f32_e32 v67, 0xbb000000, v41
	v_fmac_f32_e32 v66, 0xbb000000, v41
	v_mul_f32_e32 v70, v67, v67
	v_mul_f32_e32 v40, 0x3b000000, v41
	v_fmac_f32_e32 v70, v66, v66
	v_fmac_f32_e32 v68, 0xbb000000, v41
	v_fmac_f32_e32 v70, v68, v68
	v_fmac_f32_e32 v69, 0xbb000000, v41
	v_pk_add_f32 v[2:3], v[2:3], v[40:41] op_sel_hi:[1,0] neg_lo:[0,1] neg_hi:[0,1]
	v_fmac_f32_e32 v70, v69, v69
	v_pk_mul_f32 v[42:43], v[2:3], v[2:3]
	s_nop 0
	v_add_f32_e32 v41, v43, v70
	v_pk_add_f32 v[4:5], v[4:5], v[40:41] op_sel_hi:[1,0] neg_lo:[0,1] neg_hi:[0,1]
	v_add_f32_e32 v42, v42, v41
	v_pk_mul_f32 v[40:41], v[4:5], v[4:5]
	s_nop 0
	v_add_f32_e32 v41, v41, v42
	v_add_f32_e32 v40, v40, v41
	ds_bpermute_b32 v41, v26, v40
	s_waitcnt lgkmcnt(0)
	v_add_f32_e32 v40, v40, v41
	ds_bpermute_b32 v41, v27, v40
	s_waitcnt lgkmcnt(0)
	v_add_f32_e32 v40, v40, v41
	ds_bpermute_b32 v41, v28, v40
	s_waitcnt lgkmcnt(0)
	v_add_f32_e32 v40, v40, v41
	ds_bpermute_b32 v41, v29, v40
	s_waitcnt lgkmcnt(0)
	v_add_f32_e32 v40, v40, v41
	ds_bpermute_b32 v41, v30, v40
	s_waitcnt lgkmcnt(0)
	v_add_f32_e32 v40, v40, v41
	ds_bpermute_b32 v41, v31, v40
	s_waitcnt lgkmcnt(0)
	v_add_f32_e32 v40, v40, v41
	v_fmamk_f32 v40, v40, 0x3b000000, v199
	v_cmp_gt_f32_e32 vcc, s12, v40
	v_mul_f32_e32 v41, 0x4b800000, v40
	s_nop 0
	v_cndmask_b32_e32 v40, v40, v41, vcc
	v_rsq_f32_e32 v40, v40
	s_nop 0
	v_mul_f32_e32 v41, 0x45800000, v40
	v_cndmask_b32_e32 v40, v40, v41, vcc
	v_mul_f32_e32 v41, v66, v40
	v_fma_f32 v41, v10, v41, v11
	v_cvt_pk_bf16_f32 v41, v44, v41
	v_mul_f32_e32 v3, v3, v40
	ds_write2_b32 v35, v33, v41 offset1:1
	v_mul_f32_e32 v33, v67, v40
	v_fma_f32 v3, v18, v3, v19
	v_mul_f32_e32 v2, v2, v40
	v_fma_f32 v33, v12, v33, v13
	v_cvt_pk_bf16_f32 v3, v62, v3
	v_fma_f32 v2, v20, v2, v21
	v_cvt_pk_bf16_f32 v33, v45, v33
	ds_write2_b32 v32, v7, v3 offset1:1
	v_cvt_pk_bf16_f32 v2, v63, v2
	v_cvt_pk_bf16_f32 v3, v6, v57
	ds_write2_b32 v37, v34, v33 offset1:1
	v_mul_f32_e32 v33, v68, v40
	ds_write2_b32 v47, v3, v2 offset1:1
	v_mul_f32_e32 v2, v5, v40
	v_fma_f32 v33, v14, v33, v15
	v_fma_f32 v2, v22, v2, v23
	v_cvt_pk_bf16_f32 v33, v60, v33
	v_cvt_pk_bf16_f32 v34, v36, v54
	v_cvt_pk_bf16_f32 v2, v64, v2
	v_cvt_pk_bf16_f32 v3, v48, v58
	ds_write2_b32 v39, v34, v33 offset1:1
	v_mul_f32_e32 v33, v69, v40
	ds_write2_b32 v49, v3, v2 offset1:1
	v_mul_f32_e32 v2, v4, v40
	v_fma_f32 v33, v16, v33, v17
	v_fma_f32 v2, v24, v2, v25
	v_cvt_pk_bf16_f32 v33, v61, v33
	v_cvt_pk_bf16_f32 v34, v38, v55
	v_cvt_pk_bf16_f32 v2, v65, v2
	v_cvt_pk_bf16_f32 v3, v50, v59
	v_add_u32_e32 v32, 8, v32
	ds_write2_b32 v46, v34, v33 offset1:1
	ds_write2_b32 v51, v3, v2 offset1:1
	s_cbranch_scc0 .LBB0_519
; #define LAS __attribute__((address_space(3)))
; DEV f32x4 mma(bf16x8 bt, bf16x8 a, f32x4 acc) { return __builtin_amdgcn_mfma_f32_16x16x32_bf16(bt, a, acc, 0, 0, 0); }
; DEV void gmlp_unit(LAS unsigned char* lds, const P& p, int c, int g) {
;     ...
;     __syncthreads();
; #pragma unroll 1
;     for (int half = 0; half < 2; ++half) {
;         f32x4 acc[4][4];
; #pragma unroll
;         for (int a = 0; a < 4; ++a)
; #pragma unroll
;             for (int b = 0; b < 4; ++b) acc[a][b] = (f32x4){0.f, 0.f, 0.f, 0.f};
;         const int nks = half ? 4 : 2;
; #pragma unroll 1
;         for (int ks = 0; ks < nks; ++ks) {
;             bf16x8 bt[4], af[4];
; #pragma unroll
;             for (int nt = 0; nt < 4; ++nt) { const LAS unsigned* bp = (const LAS unsigned*)(VnT + (wid * 64 + nt * 16 + fr) * VS + ks * 32 + fq * 8);
;                 u32x4 w; w.x = bp[0]; w.y = bp[1]; w.z = bp[2]; w.w = bp[3]; bt[nt] = __builtin_bit_cast(bf16x8, w); }
; #pragma unroll
;             for (int mt = 0; mt < 4; ++mt) af[mt] = *(const bf16x8*)(TRIL + (size_t)(g * 128 + (half * 4 + mt) * 16 + fr) * 128 + ks * 32 + fq * 8);
; #pragma unroll
;             for (int mt = 0; mt < 4; ++mt)
; #pragma unroll
;                 for (int nt = 0; nt < 4; ++nt) acc[mt][nt] = mma(bt[nt], af[mt], acc[mt][nt]);
;         }
;         u32x2 uv4[4][4]; float bsv[4];
; #pragma unroll
;         for (int mt = 0; mt < 4; ++mt) { const int i = (half * 4 + mt) * 16 + fr; bsv[mt] = p.gm_bs[g * 128 + i]; const size_t pos = (size_t)(c * 128 + i);
; #pragma unroll
;             for (int nt = 0; nt < 4; ++nt) uv4[mt][nt] = *(const u32x2*)(UV + pos * 4096 + g * 512 + wid * 64 + nt * 16 + fq * 4); }
	v_readlane_b32 s12, v251, 13
	s_lshl_b32 s0, s9, 5
	v_and_b32_e32 v0, 48, v8
	v_mov_b32_e32 v1, v161
	v_readlane_b32 s13, v251, 14
	s_and_b32 s11, s0, 0xffffff80
	s_and_b32 s0, s10, 0xffffffc0
	v_lshl_add_u64 v[64:65], s[12:13], 0, v[0:1]
	s_lshl_b32 s12, s4, 7
	s_lshl_b32 s1, s5, 1
	v_readlane_b32 s14, v250, 11
	v_readlane_b32 s15, v250, 12
	s_add_u32 s13, s14, s1
	s_addc_u32 s16, s15, 0
	s_ashr_i32 s1, s0, 31
	s_lshl_b64 s[14:15], s[0:1], 1
	s_add_u32 s14, s13, s14
	v_lshrrev_b32_e32 v2, 4, v8
	s_addc_u32 s15, s16, s15
	s_add_i32 s0, s0, s5
	v_and_b32_e32 v81, 15, v9
	v_lshl_or_b32 v0, v2, 2, s0
	s_lshl_b32 s0, s4, 14
	v_lshlrev_b32_e32 v160, 3, v2
	v_lshl_or_b32 v2, v81, 7, s0
	v_readlane_b32 s0, v250, 13
	v_ashrrev_i32_e32 v1, 31, v0
	v_readlane_b32 s1, v250, 14
	v_and_b32_e32 v3, 48, v9
	v_lshl_add_u64 v[66:67], s[14:15], 0, v[160:161]
	v_lshl_add_u64 v[68:69], v[0:1], 1, s[0:1]
	s_lshr_b32 s0, s10, 6
	s_mulk_i32 s0, 0x4100
	v_mov_b32_e32 v0, s0
	s_movk_i32 s0, 0x104
	v_mad_u32_u24 v0, v81, s0, v0
	v_or_b32_e32 v89, s11, v81
	s_or_b32 s13, s11, 16
	s_or_b32 s14, s11, 32
	s_or_b32 s15, s11, 48
	v_add3_u32 v103, v0, v3, 0
	s_mov_b64 s[4:5], -1
	v_lshlrev_b32_e32 v108, 1, v2
	s_mov_b32 s10, 0
	s_waitcnt lgkmcnt(0)
	s_barrier

; #define LAS __attribute__((address_space(3)))
; DEV f32x4 mma(bf16x8 bt, bf16x8 a, f32x4 acc) { return __builtin_amdgcn_mfma_f32_16x16x32_bf16(bt, a, acc, 0, 0, 0); }
; DEV u32x2 pack4(f32x4 a) { u32x2 w; w.x = cvt_pk_bf16(a[0], a[1]); w.y = cvt_pk_bf16(a[2], a[3]); return w; }
; DEV f32x4 unpack4(u32x2 w) { return (f32x4){bflo(w.x), bfhi(w.x), bflo(w.y), bfhi(w.y)}; }
; DEV void gmlp_unit(LAS unsigned char* lds, const P& p, int c, int g) {
;     ...
; #pragma unroll 1
;         for (int ks = 0; ks < nks; ++ks) {
;             bf16x8 bt[4], af[4];
; #pragma unroll
;             for (int nt = 0; nt < 4; ++nt) { const LAS unsigned* bp = (const LAS unsigned*)(VnT + (wid * 64 + nt * 16 + fr) * VS + ks * 32 + fq * 8);
;                 u32x4 w; w.x = bp[0]; w.y = bp[1]; w.z = bp[2]; w.w = bp[3]; bt[nt] = __builtin_bit_cast(bf16x8, w); }
; #pragma unroll
;             for (int mt = 0; mt < 4; ++mt) af[mt] = *(const bf16x8*)(TRIL + (size_t)(g * 128 + (half * 4 + mt) * 16 + fr) * 128 + ks * 32 + fq * 8);
; #pragma unroll
;             for (int mt = 0; mt < 4; ++mt)
; #pragma unroll
;                 for (int nt = 0; nt < 4; ++nt) acc[mt][nt] = mma(bt[nt], af[mt], acc[mt][nt]);
;         }
;         u32x2 uv4[4][4]; float bsv[4];
; #pragma unroll
;         for (int mt = 0; mt < 4; ++mt) { const int i = (half * 4 + mt) * 16 + fr; bsv[mt] = p.gm_bs[g * 128 + i]; const size_t pos = (size_t)(c * 128 + i);
; #pragma unroll
;             for (int nt = 0; nt < 4; ++nt) uv4[mt][nt] = *(const u32x2*)(UV + pos * 4096 + g * 512 + wid * 64 + nt * 16 + fq * 4); }
; #pragma unroll
;         for (int mt = 0; mt < 4; ++mt) { const int i = (half * 4 + mt) * 16 + fr; const size_t pos = (size_t)(c * 128 + i);
; #pragma unroll
;             for (int nt = 0; nt < 4; ++nt) { const int d = g * 512 + wid * 64 + nt * 16 + fq * 4;
;                 *(u32x2*)(MIX + pos * 4096 + d) = pack4(unpack4(uv4[mt][nt]) * (acc[mt][nt] + bsv[mt])); } }
.LBB0_522:
	v_lshl_add_u64 v[78:79], s[72:73], 1, v[70:71]
	ds_read2_b32 v[74:75], v72 offset1:1
	ds_read2_b32 v[76:77], v72 offset0:2 offset1:3
	global_load_dwordx4 v[82:85], v[78:79], off
	v_add_u32_e32 v73, 0x1040, v72
	v_add_u32_e32 v87, 0x2088, v72
	v_add_u32_e32 v100, 0x30c8, v72
	v_add_u32_e32 v80, 0x1048, v72
	v_add_u32_e32 v86, 0x2080, v72
	v_add_u32_e32 v88, 0x30c0, v72
	ds_read2_b32 v[90:91], v73 offset1:1
	ds_read2_b32 v[92:93], v80 offset1:1
	ds_read2_b32 v[94:95], v86 offset1:1
	ds_read2_b32 v[96:97], v87 offset1:1
	ds_read2_b32 v[98:99], v88 offset1:1
	ds_read2_b32 v[100:101], v100 offset1:1
	v_add_co_u32_e32 v86, vcc, s33, v78
	s_add_i32 s4, s4, -1
	s_nop 0
	v_addc_co_u32_e32 v87, vcc, 0, v79, vcc
	v_add_co_u32_e32 v78, vcc, s80, v78
	s_add_i32 s72, s72, 32
	s_nop 0
	v_addc_co_u32_e32 v79, vcc, 0, v79, vcc
	s_cmp_eq_u32 s4, 0
	v_add_u32_e32 v72, 64, v72
	global_load_dwordx4 v[104:107], v[86:87], off offset:-4096
	global_load_dwordx4 v[110:113], v[86:87], off
	global_load_dwordx4 v[114:117], v[78:79], off
	s_waitcnt vmcnt(3) lgkmcnt(6)
	v_mfma_f32_16x16x32_bf16 v[60:63], v[74:77], v[82:85], v[60:63]
	s_waitcnt lgkmcnt(4)
	v_mfma_f32_16x16x32_bf16 v[56:59], v[90:93], v[82:85], v[56:59]
	s_waitcnt lgkmcnt(2)
	v_mfma_f32_16x16x32_bf16 v[52:55], v[94:97], v[82:85], v[52:55]
	s_waitcnt lgkmcnt(0)
	v_mfma_f32_16x16x32_bf16 v[48:51], v[98:101], v[82:85], v[48:51]
	s_waitcnt vmcnt(2)
	v_mfma_f32_16x16x32_bf16 v[44:47], v[74:77], v[104:107], v[44:47]
	v_mfma_f32_16x16x32_bf16 v[40:43], v[90:93], v[104:107], v[40:43]
	v_mfma_f32_16x16x32_bf16 v[36:39], v[94:97], v[104:107], v[36:39]
	v_mfma_f32_16x16x32_bf16 v[32:35], v[98:101], v[104:107], v[32:35]
	s_waitcnt vmcnt(1)
	v_mfma_f32_16x16x32_bf16 v[28:31], v[74:77], v[110:113], v[28:31]
	v_mfma_f32_16x16x32_bf16 v[24:27], v[90:93], v[110:113], v[24:27]
	v_mfma_f32_16x16x32_bf16 v[20:23], v[94:97], v[110:113], v[20:23]
	v_mfma_f32_16x16x32_bf16 v[16:19], v[98:101], v[110:113], v[16:19]
	s_waitcnt vmcnt(0)
	v_mfma_f32_16x16x32_bf16 v[12:15], v[74:77], v[114:117], v[12:15]
	v_mfma_f32_16x16x32_bf16 v[8:11], v[90:93], v[114:117], v[8:11]
	v_mfma_f32_16x16x32_bf16 v[4:7], v[94:97], v[114:117], v[4:7]
	v_mfma_f32_16x16x32_bf16 v[0:3], v[98:101], v[114:117], v[0:3]
	s_cbranch_scc0 .LBB0_522
	s_lshl_b32 s4, s10, 6
	v_or_b32_e32 v74, s4, v81
	v_readlane_b32 s16, v251, 21
	v_or_b32_e32 v160, s12, v74
	v_readlane_b32 s22, v251, 27
	v_readlane_b32 s23, v251, 28
	v_or_b32_e32 v72, s13, v74
	v_ashrrev_i32_e32 v73, 31, v72
	v_lshl_add_u64 v[70:71], v[160:161], 2, s[22:23]
	global_load_dword v102, v[70:71], off
	v_or_b32_e32 v70, s11, v74
	v_ashrrev_i32_e32 v71, 31, v70
	v_lshlrev_b64 v[70:71], 13, v[70:71]
	v_lshl_add_u64 v[70:71], v[66:67], 0, v[70:71]
	global_load_dwordx2 v[110:111], v[70:71], off
	global_load_dwordx2 v[112:113], v[70:71], off offset:32
	global_load_dwordx2 v[106:107], v[70:71], off offset:64
	global_load_dwordx2 v[104:105], v[70:71], off offset:96
	v_add_u32_e32 v160, s12, v74
	v_lshl_add_u64 v[70:71], v[160:161], 2, s[22:23]
	global_load_dword v88, v[70:71], off offset:64
	v_lshlrev_b64 v[72:73], 13, v[72:73]
	v_lshl_add_u64 v[72:73], v[66:67], 0, v[72:73]
	global_load_dwordx2 v[100:101], v[72:73], off
	global_load_dwordx2 v[98:99], v[72:73], off offset:32
	global_load_dwordx2 v[94:95], v[72:73], off offset:64
	global_load_dwordx2 v[92:93], v[72:73], off offset:96
	global_load_dword v80, v[70:71], off offset:128
	v_or_b32_e32 v72, s14, v74
	v_ashrrev_i32_e32 v73, 31, v72
	v_lshlrev_b64 v[72:73], 13, v[72:73]
	v_lshl_add_u64 v[72:73], v[66:67], 0, v[72:73]
	global_load_dwordx2 v[90:91], v[72:73], off
	global_load_dwordx2 v[86:87], v[72:73], off offset:32
	global_load_dwordx2 v[84:85], v[72:73], off offset:64
	global_load_dwordx2 v[82:83], v[72:73], off offset:96
	s_nop 0
	global_load_dword v70, v[70:71], off offset:192
	v_or_b32_e32 v72, s15, v74
	v_ashrrev_i32_e32 v73, 31, v72
	v_lshlrev_b64 v[72:73], 13, v[72:73]
	v_lshl_add_u64 v[72:73], v[66:67], 0, v[72:73]
	global_load_dwordx2 v[78:79], v[72:73], off
	global_load_dwordx2 v[76:77], v[72:73], off offset:32
	global_load_dwordx2 v[74:75], v[72:73], off offset:64
	s_nop 0
	global_load_dwordx2 v[72:73], v[72:73], off offset:96
	v_or_b32_e32 v96, s4, v89
	v_ashrrev_i32_e32 v97, 31, v96
	v_lshlrev_b64 v[114:115], 13, v[96:97]
	s_mov_b32 s10, 1
	s_mov_b64 s[4:5], 0
	s_and_b64 vcc, exec, s[0:1]
	v_readlane_b32 s17, v251, 22
	v_readlane_b32 s18, v251, 23
	v_readlane_b32 s19, v251, 24
	v_readlane_b32 s20, v251, 25
	v_readlane_b32 s21, v251, 26
	v_readlane_b32 s24, v251, 29
	v_readlane_b32 s25, v251, 30
	v_readlane_b32 s26, v251, 31
	v_readlane_b32 s27, v251, 32
	v_readlane_b32 s28, v251, 33
	v_readlane_b32 s29, v251, 34
	v_readlane_b32 s30, v251, 35
	v_readlane_b32 s31, v251, 36
	s_waitcnt vmcnt(19)
	v_pk_add_f32 v[62:63], v[62:63], v[102:103] op_sel_hi:[1,0]
	v_pk_add_f32 v[60:61], v[60:61], v[102:103] op_sel_hi:[1,0]
	s_waitcnt vmcnt(18)
	v_lshlrev_b32_e32 v116, 16, v110
	v_and_b32_e32 v117, 0xffff0000, v110
	v_lshlrev_b32_e32 v110, 16, v111
	v_and_b32_e32 v111, 0xffff0000, v111
	v_pk_mul_f32 v[62:63], v[62:63], v[110:111]
	v_pk_mul_f32 v[60:61], v[60:61], v[116:117]
	v_cvt_pk_bf16_f32 v111, v62, v63
	v_cvt_pk_bf16_f32 v110, v60, v61
	v_lshl_add_u64 v[60:61], v[68:69], 0, v[114:115]
	global_store_dwordx2 v[60:61], v[110:111], off
	s_waitcnt vmcnt(18)
	v_lshlrev_b32_e32 v62, 16, v112
	v_and_b32_e32 v63, 0xffff0000, v112
	v_lshlrev_b32_e32 v110, 16, v113
	v_and_b32_e32 v111, 0xffff0000, v113
	v_pk_add_f32 v[58:59], v[58:59], v[102:103] op_sel_hi:[1,0]
	v_pk_add_f32 v[56:57], v[56:57], v[102:103] op_sel_hi:[1,0]
	v_pk_mul_f32 v[58:59], v[58:59], v[110:111]
	v_pk_mul_f32 v[56:57], v[56:57], v[62:63]
	v_pk_add_f32 v[54:55], v[54:55], v[102:103] op_sel_hi:[1,0]
	v_cvt_pk_bf16_f32 v56, v56, v57
	v_cvt_pk_bf16_f32 v57, v58, v59
	global_store_dwordx2 v[60:61], v[56:57], off offset:32
	s_waitcnt vmcnt(18)
; DEV u32x2 pack4(f32x4 a) { u32x2 w; w.x = cvt_pk_bf16(a[0], a[1]); w.y = cvt_pk_bf16(a[2], a[3]); return w; }
; DEV f32x4 unpack4(u32x2 w) { return (f32x4){bflo(w.x), bfhi(w.x), bflo(w.y), bfhi(w.y)}; }
; DEV void gmlp_unit(LAS unsigned char* lds, const P& p, int c, int g) {
;     ...
; #pragma unroll
;         for (int mt = 0; mt < 4; ++mt) { const int i = (half * 4 + mt) * 16 + fr; bsv[mt] = p.gm_bs[g * 128 + i]; const size_t pos = (size_t)(c * 128 + i);
; #pragma unroll
;             for (int nt = 0; nt < 4; ++nt) uv4[mt][nt] = *(const u32x2*)(UV + pos * 4096 + g * 512 + wid * 64 + nt * 16 + fq * 4); }
; #pragma unroll
;         for (int mt = 0; mt < 4; ++mt) { const int i = (half * 4 + mt) * 16 + fr; const size_t pos = (size_t)(c * 128 + i);
; #pragma unroll
;             for (int nt = 0; nt < 4; ++nt) { const int d = g * 512 + wid * 64 + nt * 16 + fq * 4;
;                 *(u32x2*)(MIX + pos * 4096 + d) = pack4(unpack4(uv4[mt][nt]) * (acc[mt][nt] + bsv[mt])); } }
	v_lshlrev_b32_e32 v56, 16, v106
	v_and_b32_e32 v57, 0xffff0000, v106
	v_lshlrev_b32_e32 v58, 16, v107
	v_and_b32_e32 v59, 0xffff0000, v107
	v_pk_add_f32 v[52:53], v[52:53], v[102:103] op_sel_hi:[1,0]
	v_pk_mul_f32 v[54:55], v[54:55], v[58:59]
	v_pk_mul_f32 v[52:53], v[52:53], v[56:57]
	v_pk_add_f32 v[50:51], v[50:51], v[102:103] op_sel_hi:[1,0]
	v_cvt_pk_bf16_f32 v52, v52, v53
	v_cvt_pk_bf16_f32 v53, v54, v55
	global_store_dwordx2 v[60:61], v[52:53], off offset:64
	s_waitcnt vmcnt(18)
	v_lshlrev_b32_e32 v52, 16, v104
	v_and_b32_e32 v53, 0xffff0000, v104
	v_lshlrev_b32_e32 v54, 16, v105
	v_and_b32_e32 v55, 0xffff0000, v105
	v_pk_add_f32 v[48:49], v[48:49], v[102:103] op_sel_hi:[1,0]
	v_pk_mul_f32 v[50:51], v[50:51], v[54:55]
	v_pk_mul_f32 v[48:49], v[48:49], v[52:53]
	s_waitcnt vmcnt(16)
	v_lshlrev_b32_e32 v52, 16, v101
	v_cvt_pk_bf16_f32 v48, v48, v49
	v_cvt_pk_bf16_f32 v49, v50, v51
	global_store_dwordx2 v[60:61], v[48:49], off offset:96
	v_or_b32_e32 v48, 16, v96
	v_ashrrev_i32_e32 v49, 31, v48
	v_lshlrev_b32_e32 v50, 16, v100
	v_and_b32_e32 v51, 0xffff0000, v100
	v_and_b32_e32 v53, 0xffff0000, v101
	v_pk_add_f32 v[46:47], v[46:47], v[88:89] op_sel_hi:[1,0]
	v_pk_add_f32 v[44:45], v[44:45], v[88:89] op_sel_hi:[1,0]
	v_lshlrev_b64 v[48:49], 13, v[48:49]
	v_pk_mul_f32 v[46:47], v[46:47], v[52:53]
	v_pk_mul_f32 v[44:45], v[44:45], v[50:51]
	v_pk_add_f32 v[42:43], v[42:43], v[88:89] op_sel_hi:[1,0]
	v_cvt_pk_bf16_f32 v44, v44, v45
	v_cvt_pk_bf16_f32 v45, v46, v47
	v_lshl_add_u64 v[46:47], v[68:69], 0, v[48:49]
	global_store_dwordx2 v[46:47], v[44:45], off
	s_waitcnt vmcnt(17)
	v_lshlrev_b32_e32 v44, 16, v98
	v_and_b32_e32 v45, 0xffff0000, v98
	v_lshlrev_b32_e32 v48, 16, v99
	v_and_b32_e32 v49, 0xffff0000, v99
	v_pk_add_f32 v[40:41], v[40:41], v[88:89] op_sel_hi:[1,0]
	v_pk_mul_f32 v[42:43], v[42:43], v[48:49]
	v_pk_mul_f32 v[40:41], v[40:41], v[44:45]
	v_pk_add_f32 v[38:39], v[38:39], v[88:89] op_sel_hi:[1,0]
	v_cvt_pk_bf16_f32 v40, v40, v41
	v_cvt_pk_bf16_f32 v41, v42, v43
	global_store_dwordx2 v[46:47], v[40:41], off offset:32
	s_waitcnt vmcnt(17)
	v_lshlrev_b32_e32 v40, 16, v94
	v_and_b32_e32 v41, 0xffff0000, v94
	v_lshlrev_b32_e32 v42, 16, v95
	v_and_b32_e32 v43, 0xffff0000, v95
	v_pk_add_f32 v[36:37], v[36:37], v[88:89] op_sel_hi:[1,0]
	v_pk_mul_f32 v[38:39], v[38:39], v[42:43]
	v_pk_mul_f32 v[36:37], v[36:37], v[40:41]
	v_pk_add_f32 v[34:35], v[34:35], v[88:89] op_sel_hi:[1,0]
	v_cvt_pk_bf16_f32 v36, v36, v37
	v_cvt_pk_bf16_f32 v37, v38, v39
	global_store_dwordx2 v[46:47], v[36:37], off offset:64
	s_waitcnt vmcnt(17)
	v_lshlrev_b32_e32 v36, 16, v92
	v_and_b32_e32 v37, 0xffff0000, v92
	v_lshlrev_b32_e32 v38, 16, v93
	v_and_b32_e32 v39, 0xffff0000, v93
	v_pk_add_f32 v[32:33], v[32:33], v[88:89] op_sel_hi:[1,0]
	v_pk_mul_f32 v[34:35], v[34:35], v[38:39]
	v_pk_mul_f32 v[32:33], v[32:33], v[36:37]
	s_waitcnt vmcnt(15)
	v_lshlrev_b32_e32 v36, 16, v91
	v_cvt_pk_bf16_f32 v32, v32, v33
	v_cvt_pk_bf16_f32 v33, v34, v35
	global_store_dwordx2 v[46:47], v[32:33], off offset:96
	v_or_b32_e32 v32, 32, v96
	v_ashrrev_i32_e32 v33, 31, v32
	v_lshlrev_b32_e32 v34, 16, v90
	v_and_b32_e32 v35, 0xffff0000, v90
	v_and_b32_e32 v37, 0xffff0000, v91
	v_pk_add_f32 v[30:31], v[30:31], v[80:81] op_sel_hi:[1,0]
	v_pk_add_f32 v[28:29], v[28:29], v[80:81] op_sel_hi:[1,0]
	v_lshlrev_b64 v[32:33], 13, v[32:33]
	v_pk_mul_f32 v[30:31], v[30:31], v[36:37]
	v_pk_mul_f32 v[28:29], v[28:29], v[34:35]
	v_pk_add_f32 v[26:27], v[26:27], v[80:81] op_sel_hi:[1,0]
	v_cvt_pk_bf16_f32 v28, v28, v29
	v_cvt_pk_bf16_f32 v29, v30, v31
	v_lshl_add_u64 v[30:31], v[68:69], 0, v[32:33]
	global_store_dwordx2 v[30:31], v[28:29], off
	s_waitcnt vmcnt(16)
; DEV u32x2 pack4(f32x4 a) { u32x2 w; w.x = cvt_pk_bf16(a[0], a[1]); w.y = cvt_pk_bf16(a[2], a[3]); return w; }
; DEV f32x4 unpack4(u32x2 w) { return (f32x4){bflo(w.x), bfhi(w.x), bflo(w.y), bfhi(w.y)}; }
; DEV void gmlp_unit(LAS unsigned char* lds, const P& p, int c, int g) {
;     ...
; #pragma unroll
;         for (int mt = 0; mt < 4; ++mt) { const int i = (half * 4 + mt) * 16 + fr; bsv[mt] = p.gm_bs[g * 128 + i]; const size_t pos = (size_t)(c * 128 + i);
; #pragma unroll
;             for (int nt = 0; nt < 4; ++nt) uv4[mt][nt] = *(const u32x2*)(UV + pos * 4096 + g * 512 + wid * 64 + nt * 16 + fq * 4); }
; #pragma unroll
;         for (int mt = 0; mt < 4; ++mt) { const int i = (half * 4 + mt) * 16 + fr; const size_t pos = (size_t)(c * 128 + i);
; #pragma unroll
;             for (int nt = 0; nt < 4; ++nt) { const int d = g * 512 + wid * 64 + nt * 16 + fq * 4;
;                 *(u32x2*)(MIX + pos * 4096 + d) = pack4(unpack4(uv4[mt][nt]) * (acc[mt][nt] + bsv[mt])); } }
; DEV void run_phase(const P& p, int ph, LAS unsigned char* lds) {
;     ...
;         for (int u = bx; u < 256; u += G) gmlp_unit(lds, p, u >> 2, u & 3);
	v_lshlrev_b32_e32 v28, 16, v86
	v_and_b32_e32 v29, 0xffff0000, v86
	v_lshlrev_b32_e32 v32, 16, v87
	v_and_b32_e32 v33, 0xffff0000, v87
	v_pk_add_f32 v[24:25], v[24:25], v[80:81] op_sel_hi:[1,0]
	v_pk_mul_f32 v[26:27], v[26:27], v[32:33]
	v_pk_mul_f32 v[24:25], v[24:25], v[28:29]
	v_pk_add_f32 v[22:23], v[22:23], v[80:81] op_sel_hi:[1,0]
	v_cvt_pk_bf16_f32 v24, v24, v25
	v_cvt_pk_bf16_f32 v25, v26, v27
	global_store_dwordx2 v[30:31], v[24:25], off offset:32
	s_waitcnt vmcnt(16)
	v_lshlrev_b32_e32 v24, 16, v84
	v_and_b32_e32 v25, 0xffff0000, v84
	v_lshlrev_b32_e32 v26, 16, v85
	v_and_b32_e32 v27, 0xffff0000, v85
	v_pk_add_f32 v[20:21], v[20:21], v[80:81] op_sel_hi:[1,0]
	v_pk_mul_f32 v[22:23], v[22:23], v[26:27]
	v_pk_mul_f32 v[20:21], v[20:21], v[24:25]
	v_pk_add_f32 v[18:19], v[18:19], v[80:81] op_sel_hi:[1,0]
	v_cvt_pk_bf16_f32 v20, v20, v21
	v_cvt_pk_bf16_f32 v21, v22, v23
	global_store_dwordx2 v[30:31], v[20:21], off offset:64
	s_waitcnt vmcnt(16)
	v_lshlrev_b32_e32 v20, 16, v82
	v_and_b32_e32 v21, 0xffff0000, v82
	v_lshlrev_b32_e32 v22, 16, v83
	v_and_b32_e32 v23, 0xffff0000, v83
	v_pk_add_f32 v[16:17], v[16:17], v[80:81] op_sel_hi:[1,0]
	v_pk_mul_f32 v[18:19], v[18:19], v[22:23]
	v_pk_mul_f32 v[16:17], v[16:17], v[20:21]
	s_waitcnt vmcnt(14)
	v_lshlrev_b32_e32 v20, 16, v79
	v_cvt_pk_bf16_f32 v16, v16, v17
	v_cvt_pk_bf16_f32 v17, v18, v19
	global_store_dwordx2 v[30:31], v[16:17], off offset:96
	v_or_b32_e32 v16, 48, v96
	v_ashrrev_i32_e32 v17, 31, v16
	v_lshlrev_b32_e32 v18, 16, v78
	v_and_b32_e32 v19, 0xffff0000, v78
	v_and_b32_e32 v21, 0xffff0000, v79
	v_pk_add_f32 v[14:15], v[14:15], v[70:71] op_sel_hi:[1,0]
	v_pk_add_f32 v[12:13], v[12:13], v[70:71] op_sel_hi:[1,0]
	v_lshlrev_b64 v[16:17], 13, v[16:17]
	v_pk_mul_f32 v[14:15], v[14:15], v[20:21]
	v_pk_mul_f32 v[12:13], v[12:13], v[18:19]
	v_pk_add_f32 v[10:11], v[10:11], v[70:71] op_sel_hi:[1,0]
	v_cvt_pk_bf16_f32 v12, v12, v13
	v_cvt_pk_bf16_f32 v13, v14, v15
	v_lshl_add_u64 v[14:15], v[68:69], 0, v[16:17]
	global_store_dwordx2 v[14:15], v[12:13], off
	s_waitcnt vmcnt(15)
	v_lshlrev_b32_e32 v12, 16, v76
	v_and_b32_e32 v13, 0xffff0000, v76
	v_lshlrev_b32_e32 v16, 16, v77
	v_and_b32_e32 v17, 0xffff0000, v77
	v_pk_add_f32 v[8:9], v[8:9], v[70:71] op_sel_hi:[1,0]
	v_pk_mul_f32 v[10:11], v[10:11], v[16:17]
	v_pk_mul_f32 v[8:9], v[8:9], v[12:13]
	v_pk_add_f32 v[6:7], v[6:7], v[70:71] op_sel_hi:[1,0]
	v_cvt_pk_bf16_f32 v8, v8, v9
	v_cvt_pk_bf16_f32 v9, v10, v11
	global_store_dwordx2 v[14:15], v[8:9], off offset:32
	s_waitcnt vmcnt(15)
	v_lshlrev_b32_e32 v8, 16, v74
	v_and_b32_e32 v9, 0xffff0000, v74
	v_lshlrev_b32_e32 v10, 16, v75
	v_and_b32_e32 v11, 0xffff0000, v75
	v_pk_add_f32 v[4:5], v[4:5], v[70:71] op_sel_hi:[1,0]
	v_pk_mul_f32 v[6:7], v[6:7], v[10:11]
	v_pk_mul_f32 v[4:5], v[4:5], v[8:9]
	v_pk_add_f32 v[2:3], v[2:3], v[70:71] op_sel_hi:[1,0]
	v_cvt_pk_bf16_f32 v4, v4, v5
	v_cvt_pk_bf16_f32 v5, v6, v7
	global_store_dwordx2 v[14:15], v[4:5], off offset:64
	s_waitcnt vmcnt(15)
	v_lshlrev_b32_e32 v4, 16, v72
	v_and_b32_e32 v5, 0xffff0000, v72
	v_lshlrev_b32_e32 v6, 16, v73
	v_and_b32_e32 v7, 0xffff0000, v73
	v_pk_add_f32 v[0:1], v[0:1], v[70:71] op_sel_hi:[1,0]
	v_pk_mul_f32 v[2:3], v[2:3], v[6:7]
	v_pk_mul_f32 v[0:1], v[0:1], v[4:5]
	s_nop 0
	v_cvt_pk_bf16_f32 v0, v0, v1
	v_cvt_pk_bf16_f32 v1, v2, v3
	global_store_dwordx2 v[14:15], v[0:1], off offset:96
	s_cbranch_vccz .LBB0_521
	v_readlane_b32 s0, v254, 23
	s_add_i32 s9, s9, s0
	s_add_i32 s6, s6, s7
	s_add_i32 s8, s8, s0
	s_cmpk_gt_i32 s9, 0xff
	s_barrier
	s_cbranch_scc0 .LBB0_518
